# grid barrier moved between the main in-projection GEMM and the i/f-gate GEMM: attention workgroups start the mixer without waiting for the i/f GEMM; the 128 mLSTM workgroups meet at a counter barrier
# baseline (speedup 1.0000x reference)
; #define LAS __attribute__((address_space(3)))
; __global__ void __launch_bounds__(512, 2) fwd_mega(Args a) {
;     ...
;     const int G = gridDim.x, bx = blockIdx.x, ngw = G * 8;
;     unsigned char* ws = a.ws;
;     float* ada = (float*)(ws + WS_ADA); unsigned* ctl = (unsigned*)(ws + WS_CTL); float* rowss = (float*)(ws + WS_ROWSS); float* bias2 = (float*)(ws + WS_BIAS2);
;     bf16* WinT = (bf16*)(ws + WS_WIN); bf16* WattT = (bf16*)(ws + WS_WATT); bf16* WmlT = (bf16*)(ws + WS_WML); bf16* WoutT = (bf16*)(ws + WS_WOUT); bf16* Wff1T = (bf16*)(ws + WS_WFF1); bf16* Wff2T = (bf16*)(ws + WS_WFF2);
;     float* IFg = (float*)(ws + WS_IF); bf16* U = (bf16*)(ws + WS_U); bf16* P = (bf16*)(ws + WS_P); bf16* HID = (bf16*)(ws + WS_HID); bf16* OG = (bf16*)(ws + WS_OG); bf16* YPRE = (bf16*)(ws + WS_YPRE);
;     float* LSE = (float*)(ws + WS_LSE); bf16* Hb = (bf16*)(ws + WS_H); bf16* ATT = (bf16*)(ws + WS_ATT);
;     const float* x = a.in[0]; float* out = a.out;
;     volatile LAS unsigned* bst = (volatile LAS unsigned*)(lds + LDS_BYTES - 16);
;     if (threadIdx.x == 0) { bst[0] = 0u; bst[1] = 0u; }
;     __syncthreads();
;     (void)xcd_barrier_post(ctl + 4096, bst);
.LBB0_142:
	s_or_b64 exec, exec, s[0:1]
	v_readlane_b32 s12, v251, 8
	v_readlane_b32 s13, v251, 9
	s_add_u32 s0, s12, 0xc0000
	v_readlane_b32 s14, v251, 10
	v_readlane_b32 s15, v251, 11
	v_writelane_b32 v251, s0, 46
	s_addc_u32 s0, s13, 0
	v_writelane_b32 v251, s0, 47
	s_add_u32 s0, s12, 0x100000
	v_writelane_b32 v251, s0, 48
	s_addc_u32 s0, s13, 0
	v_writelane_b32 v251, s0, 49
	s_add_u32 s0, s12, 0x2c00000
	v_writelane_b32 v251, s0, 50
	s_addc_u32 s0, s13, 0
	v_writelane_b32 v251, s0, 51
	s_add_u32 s0, s12, 0x3000000
	v_writelane_b32 v251, s0, 52
	s_addc_u32 s0, s13, 0
	s_add_u32 s86, s12, 0xb000000
	s_addc_u32 s87, s13, 0
	s_add_u32 s88, s12, 0x31000000
	s_addc_u32 s89, s13, 0
	s_add_u32 s90, s12, 0x37000000
	s_addc_u32 s91, s13, 0
	s_add_u32 s16, s12, 0x37200000
	s_addc_u32 s17, s13, 0
	s_add_u32 s92, s12, 0x3b200000
	s_addc_u32 s93, s13, 0
	s_cmpk_lt_i32 s51, 0x1300
	v_writelane_b32 v251, s0, 53
	s_cselect_b64 s[0:1], -1, 0
	v_writelane_b32 v251, s0, 54
	s_ashr_i32 s94, s51, 31
	s_ashr_i32 s95, s14, 31
	v_writelane_b32 v251, s1, 55
	s_lshr_b32 s0, s94, 29
	s_add_i32 s0, s51, s0
	s_ashr_i32 s1, s0, 3
	s_and_b32 s0, s0, -8
	s_sub_i32 s0, s51, s0
	s_add_u32 s2, s12, 0x1500000
	s_addc_u32 s3, s13, 0
	v_writelane_b32 v251, s2, 56
	s_cmpk_lt_i32 s51, 0x80
	v_mov_b32_e32 v1, 0
	v_writelane_b32 v251, s3, 57
	s_cselect_b64 s[2:3], -1, 0
	v_writelane_b32 v251, s2, 58
	v_mov_b32_e32 v250, 0x2000
	v_mov_b32_e32 v189, 1
	v_writelane_b32 v251, s3, 59
	s_lshl_b32 s2, s0, 4
	s_add_u32 s4, s12, 0x1540000
	s_addc_u32 s5, s13, 0
	v_writelane_b32 v251, s4, 60
	v_mov_b32_e32 v192, 0x358637bd
	v_mov_b32_e32 v193, 0xf149f2ca
	v_writelane_b32 v251, s5, 61
	s_add_u32 s4, s12, 0x1500080
	s_addc_u32 s5, s13, 0
	v_writelane_b32 v251, s4, 62
	v_mbcnt_hi_u32_b32 v194, -1, v70
	v_mov_b32_e32 v195, 0x41b17218
	v_writelane_b32 v251, s5, 63
	s_add_u32 s4, s12, 0x1540080
	s_addc_u32 s5, s13, 0
	v_writelane_b32 v252, s4, 0
	v_mov_b64_e32 v[166:167], 0x80
	v_mov_b64_e32 v[168:169], 0x7f
	v_writelane_b32 v252, s5, 1
	s_add_u32 s4, s12, 0xc4200
	s_addc_u32 s5, s13, 0
	s_add_u32 s96, s12, 0xc4400
	s_addc_u32 s97, s13, 0
	s_add_u32 s54, s12, 0xc4500
	s_addc_u32 s55, s13, 0
	s_add_u32 s56, s12, 0xc4600
	s_addc_u32 s57, s13, 0
	s_add_u32 s58, s12, 0xc4700
	s_addc_u32 s59, s13, 0
	s_add_u32 s60, s12, 0xc4800
	s_addc_u32 s61, s13, 0
	s_add_u32 s64, s12, 0xc4900
	v_writelane_b32 v252, s4, 2
	s_addc_u32 s65, s13, 0
	v_mov_b32_e32 v240, v1
	v_writelane_b32 v252, s5, 3
	s_add_u32 s4, s12, 0xc4a00
	s_addc_u32 s5, s13, 0
	v_writelane_b32 v252, s4, 4
	v_mov_b32_e32 v241, v1
	v_mov_b32_e32 v242, v1
	v_writelane_b32 v252, s5, 5
	s_add_u32 s4, s12, 0xc4b00
	s_addc_u32 s5, s13, 0
	v_writelane_b32 v252, s4, 6
	v_mov_b32_e32 v243, v1
	v_bfrev_b32_e32 v196, 0.5
	v_writelane_b32 v252, s5, 7
	s_add_u32 s4, s12, 0xc4c00
	s_addc_u32 s5, s13, 0
	v_writelane_b32 v252, s4, 8
	v_mov_b32_e32 v197, 0x12000000
	v_mov_b64_e32 v[170:171], 0x200
	v_writelane_b32 v252, s5, 9
	s_add_u32 s4, s12, 0xc4d00
	s_addc_u32 s5, s13, 0
	v_writelane_b32 v252, s4, 10
	v_mov_b64_e32 v[172:173], 0x1ff
	v_mov_b32_e32 v198, 0x80
	v_writelane_b32 v252, s5, 11
	s_add_u32 s4, s12, 0xc4e00
	s_addc_u32 s5, s13, 0
	v_writelane_b32 v252, s4, 12
	v_mov_b64_e32 v[174:175], 0x800
	v_mov_b64_e32 v[176:177], 0x7ff
	v_writelane_b32 v252, s5, 13
	s_add_u32 s4, s12, 0xc4f00
	s_addc_u32 s5, s13, 0
	v_writelane_b32 v252, s4, 14
	s_mov_b64 s[84:85], 0x80
	s_waitcnt lgkmcnt(0)
	v_writelane_b32 v252, s5, 15
	s_add_u32 s4, s12, 0xc5000
	s_addc_u32 s5, s13, 0
	v_writelane_b32 v252, s4, 16
	s_barrier
	s_nop 0
	v_writelane_b32 v252, s5, 17
	s_add_u32 s4, s12, 0xc5100
	s_addc_u32 s5, s13, 0
	v_writelane_b32 v252, s4, 18
	s_nop 1
	v_writelane_b32 v252, s5, 19
	s_add_u32 s4, s12, 0xc5200
	s_addc_u32 s5, s13, 0
	v_writelane_b32 v252, s4, 20
	s_nop 1
	v_writelane_b32 v252, s5, 21
	s_add_u32 s4, s12, 0xc5300
	s_addc_u32 s5, s13, 0
	v_writelane_b32 v252, s4, 22
	s_nop 1
	v_writelane_b32 v252, s5, 23
	s_add_u32 s4, s12, 0xc7400
	s_addc_u32 s5, s13, 0
	v_writelane_b32 v252, s4, 24
	s_nop 1
	v_writelane_b32 v252, s5, 25
	s_add_u32 s4, s12, 0xc7500
	s_addc_u32 s5, s13, 0
	s_lshl_b32 s3, s51, 9
	s_add_u32 s30, s12, 0x33000000
	s_addc_u32 s31, s13, 0
	s_add_u32 s48, s12, 0x35000000
	v_writelane_b32 v252, s4, 26
	s_addc_u32 s49, s13, 0
	s_lshl_b32 s50, s14, 9
	v_writelane_b32 v252, s5, 27
	s_cmpk_lt_i32 s51, 0x200
	v_writelane_b32 v252, s3, 28
	s_cselect_b64 s[4:5], -1, 0
	s_lshl_b32 s3, s0, 6
	v_writelane_b32 v252, s4, 29
	s_cmpk_lt_i32 s51, 0x800
	s_nop 0
	v_writelane_b32 v252, s5, 30
	s_cselect_b64 s[4:5], -1, 0
	v_writelane_b32 v252, s4, 31
	s_nop 1
	v_writelane_b32 v252, s5, 32
	s_lshl_b32 s4, s0, 8
	s_add_u32 s5, s12, 0x5000
	v_writelane_b32 v252, s5, 33
	s_addc_u32 s5, s13, 0
	v_writelane_b32 v252, s5, 34
	s_cmp_lt_i32 s0, 0
	s_mul_i32 s5, s0, 17
	s_cselect_b32 s2, s5, s2
	s_mul_i32 s5, s0, 0x41
	s_cselect_b32 s3, s5, s3
	s_movk_i32 s5, 0x261
	s_cselect_b32 s5, s5, 0x260
	s_mul_i32 s5, s0, s5
	s_mulk_i32 s0, 0x101
	s_cselect_b32 s8, s0, s4
	s_add_i32 s5, s5, s1
	s_mul_hi_i32 s0, s5, 0x6bca1af3
	s_lshr_b32 s4, s0, 31
	s_ashr_i32 s0, s0, 7
	s_add_i32 s0, s0, s4
	s_mul_i32 s4, s0, 0x130
	s_sub_i32 s4, s5, s4
	s_bfe_u32 s5, s4, 0x3001c
	s_add_i32 s5, s4, s5
	s_and_b32 s6, s5, 0xfff8
	s_add_i32 s3, s3, s1
	s_sub_i32 s4, s4, s6
	s_ashr_i32 s6, s3, 31
	s_lshr_b32 s6, s6, 27
	s_add_i32 s6, s3, s6
	s_and_b32 s7, s6, 0xffe0
	s_sub_i32 s3, s3, s7
	s_bfe_i32 s7, s3, 0x80000
	s_bfe_u32 s7, s7, 0x3000c
	s_add_i32 s7, s3, s7
	s_and_b32 s9, s7, 0xf8
	s_lshl_b32 s0, s0, 3
	s_sext_i32_i16 s4, s4
	s_sub_i32 s3, s3, s9
	s_add_i32 s12, s0, s4
	s_add_i32 s10, s2, s1
;     __host__ __device__ bool next(int i, Unit& u) const {
;         const long L = (long)i * G + c; if (L >= nwg) return false;
;         int wgid = (int)L; { const int q = nwg / NXCD, r = nwg % NXCD, xcd = wgid % NXCD, off = wgid / NXCD; wgid = (xcd < r ? xcd * (q + 1) : r * (q + 1) + (xcd - r) * q) + off; }
;         const int nig = WGM * nN, gid = wgid / nig, fm = gid * WGM, gsz = (nM - fm) < WGM ? (nM - fm) : WGM;
;         u.pm = fm + ((wgid % nig) % gsz); u.pn = (wgid % nig) / gsz; return true;
; template <class Epi, class Sched, bool ALIGN_EPI = false, bool SP2 = false>
; __device__ __forceinline__ void gemm_phase(PG8_LAS unsigned char* lds, const Gemm g, const Sched& S, const Epi& E) {
;     ...
;     const char* cA = (const char*)g.A + (size_t)cur.pm * tstep; const char* cB = (const char*)g.Bt + (size_t)cur.pn * tstep;
	s_ashr_i32 s0, s6, 5
	s_bfe_i32 s2, s7, 0x80000
	s_lshl_b32 s0, s0, 3
	s_sext_i32_i16 s2, s2
	s_sext_i32_i8 s3, s3
	s_add_i32 s18, s0, s3
	s_ashr_i32 s0, s2, 3
	s_sext_i32_i16 s5, s5
	v_writelane_b32 v252, s0, 35
	s_lshr_b32 s0, s2, 3
	s_bfe_i64 s[6:7], s[0:1], 0x100000
	s_ashr_i32 s0, s5, 3
	v_writelane_b32 v252, s0, 36
	s_mov_b32 s2, s10
	s_ashr_i32 s11, s10, 31
	v_writelane_b32 v252, s2, 37
	s_ashr_i32 s19, s18, 31
	s_lshr_b32 s0, s5, 3
	v_writelane_b32 v252, s3, 38
	s_lshl_b64 s[2:3], s[10:11], 19
	v_writelane_b32 v252, s2, 39
	s_lshl_b64 s[4:5], s[6:7], 18
	v_readlane_b32 s10, v251, 34
	v_writelane_b32 v252, s3, 40
	s_lshl_b64 s[2:3], s[18:19], 18
	v_readlane_b32 s11, v251, 35
	s_add_u32 s4, s10, s4
	s_addc_u32 s5, s11, s5
	s_add_u32 s10, s4, 0x20000
	s_addc_u32 s11, s5, 0
	v_writelane_b32 v252, s10, 41
	s_add_u32 s2, s92, s2
	s_addc_u32 s3, s93, s3
	v_writelane_b32 v252, s11, 42
	s_add_u32 s10, s2, 0x20000
	v_writelane_b32 v252, s2, 43
	s_addc_u32 s11, s3, 0
	s_nop 0
	v_writelane_b32 v252, s3, 44
	v_writelane_b32 v252, s10, 45
	s_add_u32 s2, s4, 0x20080
	s_nop 0
	v_writelane_b32 v252, s11, 46
	v_writelane_b32 v252, s4, 47
	s_addc_u32 s3, s5, 0
	v_readlane_b32 s10, v251, 36
	v_writelane_b32 v252, s5, 48
	v_writelane_b32 v252, s2, 49
	s_lshl_b64 s[4:5], s[6:7], 19
	v_readlane_b32 s11, v251, 37
	v_writelane_b32 v252, s3, 50
	s_lshl_b64 s[2:3], s[18:19], 19
	s_add_u32 s10, s10, s4
	s_addc_u32 s11, s11, s5
	s_add_u32 s20, s10, 0x40000
	s_addc_u32 s21, s11, 0
	v_writelane_b32 v252, s20, 51
	s_nop 1
	v_writelane_b32 v252, s21, 52
	v_writelane_b32 v252, s16, 53
	s_add_u32 s16, s16, s2
	v_writelane_b32 v252, s17, 54
	s_addc_u32 s17, s17, s3
	s_add_u32 s20, s16, 0x40000
	v_writelane_b32 v252, s16, 55
	s_addc_u32 s21, s17, 0
	s_nop 0
	v_writelane_b32 v252, s17, 56
	v_writelane_b32 v252, s20, 57
	s_add_u32 s16, s10, 0x40080
	s_nop 0
	v_writelane_b32 v252, s21, 58
	v_writelane_b32 v252, s10, 59
	s_addc_u32 s17, s11, 0
	s_add_i32 s1, s8, s1
	s_ashr_i32 s8, s1, 31
	s_lshr_b32 s8, s8, 25
	s_add_i32 s8, s1, s8
	s_and_b32 s9, s8, 0xff80
	s_sub_i32 s1, s1, s9
	s_bfe_i32 s9, s1, 0x80000
	s_bfe_u32 s9, s9, 0x3000c
	s_add_i32 s9, s1, s9
	v_writelane_b32 v252, s11, 60
	s_and_b32 s10, s9, 0xf8
	s_sub_i32 s1, s1, s10
	s_ashr_i32 s8, s8, 7
	v_writelane_b32 v252, s16, 61
	s_lshl_b32 s8, s8, 3
	s_sext_i32_i8 s1, s1
	v_writelane_b32 v252, s17, 62
	s_add_i32 s16, s8, s1
	s_bfe_i32 s9, s9, 0x80000
	s_mov_b32 s10, s16
	s_sext_i32_i16 s9, s9
	s_ashr_i32 s17, s16, 31
	v_writelane_b32 v253, s10, 0
	s_lshr_b32 s8, s9, 3
	s_ashr_i32 s1, s9, 3
	v_writelane_b32 v253, s11, 1
	s_lshl_b64 s[10:11], s[16:17], 19
	s_bfe_i64 s[8:9], s[8:9], 0x100000
	v_writelane_b32 v253, s10, 2
	s_lshl_b64 s[8:9], s[8:9], 19
	v_writelane_b32 v252, s1, 63
	v_writelane_b32 v253, s11, 3
	v_readlane_b32 s10, v251, 40
	v_readlane_b32 s11, v251, 41
	s_add_u32 s8, s10, s8
	s_addc_u32 s9, s11, s9
	s_add_u32 s10, s8, 0x40000
	s_addc_u32 s11, s9, 0
	v_writelane_b32 v253, s10, 4
	s_nop 1
	v_writelane_b32 v253, s11, 5
	s_add_u32 s10, s8, 0x40080
	v_writelane_b32 v253, s8, 6
	s_addc_u32 s11, s9, 0
	s_lshl_b64 s[6:7], s[6:7], 21
	v_writelane_b32 v253, s9, 7
	v_writelane_b32 v253, s10, 8
	s_mov_b32 s8, s18
	s_nop 0
	v_writelane_b32 v253, s11, 9
	v_writelane_b32 v253, s8, 10
	v_readlane_b32 s10, v251, 42
	v_readlane_b32 s11, v251, 43
	v_writelane_b32 v253, s9, 11
	s_lshl_b64 s[8:9], s[18:19], 21
	s_add_u32 s6, s10, s6
	s_addc_u32 s7, s11, s7
	s_add_u32 s10, s6, 0x100000
	s_addc_u32 s11, s7, 0
	v_writelane_b32 v253, s10, 12
	s_add_u32 s8, s86, s8
	s_addc_u32 s9, s87, s9
	v_writelane_b32 v253, s11, 13
	s_add_u32 s10, s8, 0x100000
	v_writelane_b32 v253, s8, 14
	s_addc_u32 s11, s9, 0
	s_nop 0
	v_writelane_b32 v253, s9, 15
	v_writelane_b32 v253, s10, 16
	s_add_u32 s8, s6, 0x100080
	s_nop 0
	v_writelane_b32 v253, s11, 17
	v_writelane_b32 v253, s6, 18
	s_addc_u32 s9, s7, 0
	s_ashr_i32 s13, s12, 31
	v_writelane_b32 v253, s7, 19
	v_writelane_b32 v253, s8, 20
	s_mov_b32 s6, s12
	s_bfe_i64 s[0:1], s[0:1], 0x100000
	v_writelane_b32 v253, s9, 21
	v_writelane_b32 v253, s6, 22
	s_lshl_b64 s[0:1], s[0:1], 19
	s_mov_b64 s[10:11], s[62:63]
	v_writelane_b32 v253, s7, 23
	s_lshl_b64 s[6:7], s[12:13], 19
	v_writelane_b32 v253, s6, 24
	s_nop 1
	v_writelane_b32 v253, s7, 25
	v_readlane_b32 s6, v251, 32
	v_readlane_b32 s7, v251, 33
	s_add_u32 s0, s6, s0
	s_addc_u32 s1, s7, s1
	s_add_u32 s6, s0, 0x40000
	s_addc_u32 s7, s1, 0
	v_writelane_b32 v253, s6, 26
	s_nop 1
; __global__ void __launch_bounds__(512, 2) fwd_mega(Args a) {
;     ...
;     if (threadIdx.x == 0) { bst[0] = 0u; bst[1] = 0u; }
;     __syncthreads();
;     (void)xcd_barrier_post(ctl + 4096, bst);
	v_writelane_b32 v253, s7, 27
	s_add_u32 s6, s0, 0x40080
	v_writelane_b32 v253, s0, 28
	s_addc_u32 s7, s1, 0
	s_nop 0
	v_writelane_b32 v253, s1, 29
	v_readlane_b32 s0, v251, 38
	v_readlane_b32 s1, v251, 39
	s_add_u32 s4, s0, s4
	s_addc_u32 s5, s1, s5
	v_writelane_b32 v253, s6, 30
	s_add_u32 s0, s4, 0x40000
	s_addc_u32 s1, s5, 0
	v_writelane_b32 v253, s7, 31
	v_writelane_b32 v253, s0, 32
	s_add_u32 s2, s88, s2
	s_addc_u32 s3, s89, s3
	v_writelane_b32 v253, s1, 33
	s_mul_i32 s0, s15, s14
	s_mul_i32 s0, s0, s33
	v_writelane_b32 v253, s0, 34
	s_add_u32 s0, s2, 0x40000
	v_writelane_b32 v253, s2, 35
	s_addc_u32 s1, s3, 0
	s_nop 0
	v_writelane_b32 v253, s3, 36
	v_writelane_b32 v253, s0, 37
	s_mov_b32 s2, 0
	s_nop 0
	v_writelane_b32 v253, s1, 38
	s_add_u32 s0, s4, 0x40080
	v_writelane_b32 v253, s4, 39
	s_addc_u32 s1, s5, 0
	s_bitcmp1_b32 s51, 0
	v_writelane_b32 v253, s5, 40
	v_writelane_b32 v253, s0, 41
	s_nop 1
	v_writelane_b32 v253, s1, 42
	s_cselect_b64 s[0:1], -1, 0
	v_writelane_b32 v253, s0, 43
	s_bitcmp1_b32 s14, 0
	s_nop 0
	v_writelane_b32 v253, s1, 44
	s_mov_b32 s0, s14
	v_writelane_b32 v253, s0, 45
	s_cselect_b64 s[0:1], -1, 0
	v_writelane_b32 v253, s0, 46
	s_nop 1
	v_writelane_b32 v253, s1, 47
	s_lshl_b32 s0, s51, 12
	v_writelane_b32 v253, s0, 48
	s_lshl_b32 s0, s14, 12
	v_writelane_b32 v253, s0, 49
	s_add_i32 s0, 0, 0x23ff0
	v_writelane_b32 v253, s0, 50
	s_add_i32 s0, 0, 0x23ff4
	v_writelane_b32 v253, s0, 51
	s_add_i32 s0, 0, 0xc800
	v_writelane_b32 v253, s0, 52
	s_add_i32 s0, 0, 0x13300
	v_writelane_b32 v253, s0, 53
	s_add_i32 s0, 0, 0x12b00
	v_writelane_b32 v253, s0, 54
	s_add_i32 s0, 0, 0x11d00
	v_writelane_b32 v253, s0, 55
	s_add_i32 s0, 0, 0x12600
	v_writelane_b32 v253, s0, 56
	s_add_i32 s0, 0, 0x11e00
	v_writelane_b32 v253, s0, 57
	s_add_i32 s0, 0, 0x11c00
	v_writelane_b32 v253, s0, 58
	s_add_i32 s0, 0, 0x11c20
	v_writelane_b32 v253, s0, 59
	s_add_i32 s0, 0, 0x11c40
	v_writelane_b32 v253, s0, 60
	s_add_i32 s0, 0, 0x11c60
	v_writelane_b32 v253, s0, 61
	s_add_i32 s0, 0, 0x11c80
	v_writelane_b32 v253, s0, 62
	s_add_i32 s0, 0, 0x11ca0
	v_writelane_b32 v253, s0, 63
	s_add_i32 s0, 0, 0x11cc0
	v_writelane_b32 v254, s0, 0
	s_add_i32 s0, 0, 0x11ce0
	v_writelane_b32 v254, s0, 1
	s_add_i32 s0, 0, 0x13600
	v_writelane_b32 v254, s0, 2
	s_add_i32 s0, 0, 0x9694
	v_writelane_b32 v254, s0, 3
	s_mov_b64 s[0:1], -1
	v_writelane_b32 v254, s0, 4
	s_mov_b64 s[14:15], s[66:67]
	s_nop 0
	v_writelane_b32 v254, s1, 5
	s_mov_b32 s1, 0
	v_writelane_b32 v254, s0, 6
	s_nop 1
	v_writelane_b32 v254, s1, 7
	s_mov_b64 s[0:1], s[52:53]
	v_writelane_b32 v254, s0, 8
	s_nop 1
	v_writelane_b32 v254, s1, 9
	v_writelane_b32 v254, s2, 10
	v_writelane_b32 v254, s3, 11
	v_writelane_b32 v254, s4, 12
	v_writelane_b32 v254, s5, 13
	v_writelane_b32 v254, s6, 14
	v_writelane_b32 v254, s7, 15
	v_writelane_b32 v254, s8, 16
	v_writelane_b32 v254, s9, 17
	v_writelane_b32 v254, s10, 18
	v_writelane_b32 v254, s11, 19
	v_writelane_b32 v254, s12, 20
	v_writelane_b32 v254, s13, 21
	v_writelane_b32 v254, s14, 22
	v_writelane_b32 v254, s15, 23
	v_writelane_b32 v254, s54, 24
	s_nop 1
	v_writelane_b32 v254, s55, 25
	v_writelane_b32 v254, s56, 26
	s_nop 1
	v_writelane_b32 v254, s57, 27
	v_writelane_b32 v254, s58, 28
	s_nop 1
	v_writelane_b32 v254, s59, 29
	v_writelane_b32 v254, s60, 30
	s_nop 1
	v_writelane_b32 v254, s61, 31
	v_writelane_b32 v254, s64, 32
	s_nop 1
	v_writelane_b32 v254, s65, 33
	v_writelane_b32 v254, s30, 34
	s_nop 1
	v_writelane_b32 v254, s31, 35
	v_writelane_b32 v254, s48, 36
	s_nop 1
	v_writelane_b32 v254, s49, 37
	v_writelane_b32 v254, s50, 38
	v_writelane_b32 v254, s51, 39
	v_writelane_b32 v254, s86, 40
	s_nop 1
	v_writelane_b32 v254, s87, 41
	v_writelane_b32 v254, s88, 42
	s_nop 1
	v_writelane_b32 v254, s89, 43
	v_writelane_b32 v254, s90, 44
	s_nop 1
	v_writelane_b32 v254, s91, 45
	v_writelane_b32 v254, s92, 46
	s_nop 1
	v_writelane_b32 v254, s93, 47
	v_writelane_b32 v254, s94, 48
	v_writelane_b32 v254, s95, 49
	v_writelane_b32 v254, s96, 50
	s_nop 1
	v_writelane_b32 v254, s97, 51
	s_getreg_b32 s98, hwreg(HW_REG_XCC_ID, 0, 4)
	s_lshl_b32 s98, 1, s98
	v_mov_b32_e32 v0, s98
	s_and_b32 s99, s51, 7
	s_lshl_b32 s99, s99, 2
	v_readlane_b32 s100, v252, 26
	v_readlane_b32 s101, v252, 27
	s_add_u32 s100, s100, s99
	s_addc_u32 s101, s101, 0
	v_cmp_eq_u32_e32 vcc, 0, v188
	s_and_saveexec_b64 s[98:99], vcc
	s_nop 3
	global_atomic_or v1, v0, s[100:101] offset:32
	s_or_b64 exec, exec, s[98:99]
	v_writelane_b32 v255, 0, 47
	s_branch .LBB0_146

; __device__ __forceinline__ unsigned xb_add(unsigned* p, unsigned v) { return __hip_atomic_fetch_add(p, v, __ATOMIC_RELAXED, __HIP_MEMORY_SCOPE_AGENT); }
; __device__ __forceinline__ void xcd_barrier(const XcdBarrier& b) {
;     asm volatile("s_waitcnt vmcnt(0)" ::: "memory");
;     __syncthreads();
;     if (threadIdx.x == 0) {
;         unsigned* bar = b.bar;
;         __builtin_amdgcn_s_waitcnt(0);
;         unsigned nloc = b.st[0], nx = b.st[1];
;         if (nloc == 0u) { xcd_barrier_complete(bar, b.x, nloc, nx); b.st[0] = nloc; b.st[1] = nx; }
;         const unsigned old = xb_add(&bar[XB_XSUB(b.x)], 1u);
; __global__ void __launch_bounds__(512, 2) fwd_mega(Args a) {
;     ...
;         __syncthreads();
.LBB0_216:
	v_writelane_b32 v255, s8, 40
	v_writelane_b32 v255, s9, 41
	v_writelane_b32 v255, s14, 42
	v_writelane_b32 v255, s16, 43
	v_writelane_b32 v255, s17, 44
	v_writelane_b32 v255, s18, 45
	v_writelane_b32 v255, s19, 46
	s_getreg_b32 s4, hwreg(HW_REG_XCC_ID, 0, 4)
	s_waitcnt vmcnt(0)
	s_waitcnt vmcnt(0)
	s_barrier
	s_mov_b64 s[2:3], exec
	v_readlane_b32 s6, v251, 12
	v_readlane_b32 s7, v251, 13
	s_and_b64 s[6:7], s[2:3], s[6:7]
	s_xor_b64 s[2:3], s[6:7], s[2:3]
	s_mov_b64 exec, s[6:7]
	s_cbranch_execz .Lgb2_307
	v_readlane_b32 s5, v253, 50
	s_waitcnt vmcnt(0) expcnt(0) lgkmcnt(0)
	s_and_b32 s10, s4, 15
	v_mov_b32_e32 v0, s5
	ds_read_b32 v3, v0
	v_readlane_b32 s5, v253, 51
	s_waitcnt lgkmcnt(0)
	v_cmp_ne_u32_e32 vcc, 0, v3
	v_mov_b32_e32 v0, s5
	ds_read_b32 v0, v0
	s_cbranch_vccnz .Lgb2_270
	s_mov_b32 s11, 1
	s_branch .Lgb2_258

; #define PG8_STAGE(bufoff, gbase, voff) do { _Pragma("unroll") for (int _i = 0; _i < 2; ++_i) \
;         __builtin_amdgcn_global_load_lds((const unsigned*)((const char*)(gbase) + (voff)[_i]), (PG8_LAS unsigned*)(lds + (bufoff) + ldsw + _i * 8192), 16, 0, 0); } while (0)
; #define PG8_WAIT_V(n) asm volatile("s_waitcnt vmcnt(" #n ")" ::: "memory")
; #define PG8_BAR __builtin_amdgcn_s_barrier()
; template <class Epi, class Sched, bool ALIGN_EPI = false, bool SP2 = false>
; __device__ __forceinline__ void gemm_phase(PG8_LAS unsigned char* lds, const Gemm g, const Sched& S, const Epi& E) {
;     ...
;     if constexpr (SP2) {
;         PG8_STAGE(PG8_SB(0, 0), cB, voffB); PG8_STAGE(PG8_SB(0, 1), cB + hstep, voffB); PG8_STAGE(PG8_SA(0, 0), cA, voffA); PG8_STAGE(PG8_SA(0, 1), cA + hstep, voffA);
;         if (wr == 1) PG8_BAR;
;         PG8_WAIT_V(2); PG8_BAR;
;         PG8_STAGE(PG8_SB(1, 0), cB + kstep, voffB); PG8_STAGE(PG8_SA(1, 0), cA + kstep, voffA); PG8_STAGE(PG8_SB(1, 1), cB + hstep + kstep, voffB);
;         PG8_WAIT_V(6); PG8_BAR;
; __global__ void __launch_bounds__(512, 2) fwd_mega(Args a) {
;     ...
;         { pg8::Gemm g{U + (size_t)grow0 * 1024, WinT + (size_t)38 * 256 * 1024, TH, 256, 1024}; pg8::StaticOrder S; S.init(TH, 256, G, bx);
;           EpiIF E{IFg + (size_t)grow0 * 16, a.in[7]};
;           pg8::gemm_phase<EpiIF, pg8::StaticOrder, true, true>(lds, g, S, E); }
.Lgb2_307:
	s_or_b64 exec, exec, s[2:3]
	s_waitcnt lgkmcnt(0)
	s_barrier
	v_readlane_b32 s8, v255, 40
	v_readlane_b32 s9, v255, 41
	v_readlane_b32 s14, v255, 42
	v_readlane_b32 s16, v255, 43
	v_readlane_b32 s17, v255, 44
	v_readlane_b32 s18, v255, 45
	v_readlane_b32 s19, v255, 46
	s_nop 3
	v_readlane_b32 s2, v251, 58
	v_readlane_b32 s3, v251, 59
	v_mov_b32_e32 v12, v188
	s_waitcnt vmcnt(0)
	v_cndmask_b32_e64 v0, 0, 1, s[2:3]
	s_barrier
	v_cmp_ne_u32_e64 s[0:1], 1, v0
	s_andn2_b64 vcc, exec, s[2:3]
	v_readfirstlane_b32 s4, v12
	s_cbranch_vccnz .LBB0_254
	v_lshlrev_b32_e32 v0, 4, v12
	v_add_u32_e32 v2, 0x2000, v0
	v_ashrrev_i32_e32 v3, 31, v2
	v_lshrrev_b32_e32 v3, 22, v3
	v_add_u32_e32 v3, v2, v3
	v_ashrrev_i32_e32 v6, 10, v3
	v_mul_i32_i24_e32 v3, 0x400, v6
	v_sub_u32_e32 v2, v2, v3
	v_lshrrev_b32_e32 v3, 4, v2
	v_bitop3_b32 v2, v3, v2, 32 bitop3:0x6c
	v_ashrrev_i32_e32 v3, 31, v2
	v_lshrrev_b32_e32 v3, 26, v3
	v_add_u32_e32 v3, v2, v3
	v_lshlrev_b32_e32 v4, 3, v6
	v_ashrrev_i32_e32 v7, 6, v3
	v_and_b32_e32 v4, -16, v4
	v_add_u32_e32 v4, v7, v4
	v_and_b32_e32 v5, 3, v7
	s_mov_b32 s2, 0x1fffe0
	v_lshrrev_b32_e32 v8, 2, v4
	v_lshlrev_b32_e32 v9, 1, v4
	v_and_b32_e32 v3, 0xc0, v3
	v_and_or_b32 v5, v4, s2, v5
	v_and_b32_e32 v8, 4, v8
	v_and_b32_e32 v9, 24, v9
	v_sub_u32_e32 v2, v2, v3
	v_or3_b32 v5, v5, v8, v9
	v_lshlrev_b32_e32 v8, 5, v6
	v_ashrrev_i16_sdwa v2, v189, sext(v2) dst_sel:DWORD dst_unused:UNUSED_PAD src0_sel:DWORD src1_sel:BYTE_0
	v_and_b32_e32 v9, 32, v8
	v_bfe_i32 v8, v2, 0, 16
	v_add_lshl_u32 v2, v9, v8, 1
	v_lshl_add_u32 v74, v5, 11, v2
	v_lshl_add_u32 v76, v4, 11, v2
	v_bfe_i32 v2, v12, 27, 1
	v_lshrrev_b32_e32 v2, 22, v2
	v_add_u32_e32 v2, v0, v2
	v_and_b32_e32 v2, 0xfffffc00, v2
	v_sub_u32_e32 v0, v0, v2
	v_lshrrev_b32_e32 v2, 4, v0
	v_ashrrev_i32_e32 v3, 31, v12
	v_bitop3_b32 v0, v2, v0, 32 bitop3:0x6c
	v_lshrrev_b32_e32 v3, 26, v3
	v_ashrrev_i32_e32 v2, 31, v0
	v_add_u32_e32 v3, v12, v3
	v_lshrrev_b32_e32 v2, 26, v2
	v_ashrrev_i32_e32 v10, 6, v3
	v_add_u32_e32 v2, v0, v2
	v_lshlrev_b32_e32 v3, 3, v10
	v_ashrrev_i32_e32 v9, 6, v2
	v_and_b32_e32 v3, -16, v3
	v_add_u32_e32 v3, v9, v3
	v_and_b32_e32 v4, 3, v9
	v_lshrrev_b32_e32 v5, 2, v3
	v_lshlrev_b32_e32 v11, 1, v3
	v_and_b32_e32 v2, 0xc0, v2
	v_and_or_b32 v4, v3, s2, v4
	v_and_b32_e32 v5, 4, v5
	v_and_b32_e32 v11, 24, v11
	v_sub_u32_e32 v0, v0, v2
	s_ashr_i32 s6, s4, 6
	v_or3_b32 v4, v4, v5, v11
	v_lshlrev_b32_e32 v5, 5, v10
	v_ashrrev_i16_sdwa v0, v189, sext(v0) dst_sel:DWORD dst_unused:UNUSED_PAD src0_sel:DWORD src1_sel:BYTE_0
	s_lshl_b32 s28, s6, 10
	v_and_b32_e32 v5, 32, v5
	v_bfe_i32 v11, v0, 0, 16
	v_add_lshl_u32 v0, v5, v11, 1
	s_add_i32 s29, s28, 0
	v_readlane_b32 s2, v251, 56
	v_lshl_add_u32 v78, v4, 11, v0
	s_add_i32 m0, s29, 0x10000
	v_readlane_b32 s3, v251, 57
	s_add_i32 s30, s29, 0x14000
	s_add_i32 s31, s29, 0x16000
	s_ashr_i32 s5, s4, 8
	v_lshl_add_u32 v0, v3, 11, v0
	v_mov_b32_e32 v77, v1
	global_load_lds_dwordx4 v78, s[2:3]
	s_add_i32 m0, s29, 0x12000
	s_nop 0
	global_load_lds_dwordx4 v74, s[2:3]
	v_readlane_b32 s2, v251, 60
	s_mov_b32 m0, s30
	v_readlane_b32 s3, v251, 61
	s_nop 4
	global_load_lds_dwordx4 v78, s[2:3]
	s_mov_b32 m0, s31
	s_nop 0
	global_load_lds_dwordx4 v74, s[2:3]
	v_readlane_b32 s2, v252, 39
	v_readlane_b32 s3, v252, 40
	s_add_u32 s20, s26, s2
	s_addc_u32 s21, s27, s3
	s_add_i32 s33, s29, 0x2000
	s_mov_b32 m0, s29
	s_add_u32 s2, s20, 0x40000
	global_load_lds_dwordx4 v0, s[20:21]
	s_mov_b32 m0, s33
	s_addc_u32 s3, s21, 0
	s_add_i32 s34, s29, 0x4000
	global_load_lds_dwordx4 v76, s[20:21]
	s_mov_b32 m0, s34
	s_add_i32 s35, s29, 0x6000
	global_load_lds_dwordx4 v0, s[2:3]
	s_mov_b32 m0, s35
	s_cmp_eq_u32 s5, 1
	global_load_lds_dwordx4 v76, s[2:3]
	v_lshl_add_u64 v[2:3], s[20:21], 0, v[0:1]
	s_cselect_b64 s[2:3], -1, 0
	s_cmp_lg_u32 s5, 1
	v_lshl_add_u64 v[4:5], s[20:21], 0, v[76:77]
	s_cbranch_scc1 .LBB0_219
	s_barrier

; #define GBAR() do { XcdBarrier xb_; xb_.bar = (unsigned*)(a.ws + WS_CTL) + 4096; xb_.x = xb_xcc_id(); xb_.st = (volatile LAS unsigned*)(lds + LDS_BYTES - 16); xcd_barrier(xb_); } while (0)
; __global__ void __launch_bounds__(512, 2) fwd_mega(Args a) {
;     ...
;         GBAR();
;     ...
;             for (int r2 = 0; r2 < REP_ML; ++r2) for (int seq = bx; seq < 128; seq += G) mlstm_seq(lds, P, IFg + (size_t)grow0 * 16, Hb, a.in[8], a.in[9], a.in[13], seq);
.LBB0_254:
	s_and_b64 vcc, exec, s[0:1]
	s_cbranch_vccnz .Lsb_done
	s_waitcnt vmcnt(0)
	s_barrier
	v_readlane_b32 s100, v252, 26
	v_readlane_b32 s101, v252, 27
	v_readlane_b32 s98, v255, 47
	s_add_i32 s98, s98, 1
	s_nop 0
	v_writelane_b32 v255, s98, 47
	s_lshl_b32 s98, s98, 7
	v_cmp_eq_u32_e32 vcc, 0, v188
	s_and_saveexec_b64 s[2:3], vcc
	s_cbranch_execz .Lsb_join
	buffer_wbl2 sc1
	s_waitcnt vmcnt(0)
	global_atomic_add v1, v189, s[100:101] offset:96
	s_waitcnt vmcnt(0)
	s_mov_b32 s99, 0
.Lsb_spin:
	global_load_dword v0, v1, s[100:101] offset:96 sc1
	s_waitcnt vmcnt(0)
	v_readfirstlane_b32 s4, v0
	s_cmp_ge_u32 s4, s98
	s_cbranch_scc1 .Lsb_got
	s_sleep 1
	s_add_i32 s99, s99, 1
	s_cmp_lt_u32 s99, 0x8000
	s_cbranch_scc1 .Lsb_spin
.Lsb_got:
	buffer_inv sc1
	s_waitcnt vmcnt(0)

; #define FRESH_IDS() int tid = threadIdx.x; asm volatile("" : "+v"(tid)); const int lane = tid & 63, wave = __builtin_amdgcn_readfirstlane(tid >> 6), gw = bx * 8 + wave; (void)lane; (void)gw
; #define GBAR() do { XcdBarrier xb_; xb_.bar = (unsigned*)(a.ws + WS_CTL) + 4096; xb_.x = xb_xcc_id(); xb_.st = (volatile LAS unsigned*)(lds + LDS_BYTES - 16); xcd_barrier(xb_); } while (0)
; __global__ void __launch_bounds__(512, 2) fwd_mega(Args a) {
;     ...
;         GBAR();
;         for (int rep = 0; rep < REP_MIX; ++rep)
;         {
;             FRESH_IDS();
;             for (int r2 = 0; r2 < REP_ML; ++r2) for (int seq = bx; seq < 128; seq += G) mlstm_seq(lds, P, IFg + (size_t)grow0 * 16, Hb, a.in[8], a.in[9], a.in[13], seq);
.Lsb_done:
	v_mov_b32_e32 v124, v188
	s_and_b64 vcc, exec, s[0:1]
	s_waitcnt lgkmcnt(0)
	s_barrier
	s_cbranch_vccnz .LBB0_398
	v_readlane_b32 s0, v254, 6
	v_readlane_b32 s1, v254, 7
	v_readlane_b32 s4, v254, 52
	s_mov_b32 s3, s1
	s_lshl_b32 s2, s4, 19
	s_lshl_b64 s[0:1], s[2:3], 2
	v_readlane_b32 s2, v251, 50
	s_add_u32 s6, s2, s0
	v_readlane_b32 s0, v251, 51
	s_addc_u32 s7, s0, s1
	v_readlane_b32 s5, v254, 53
	v_writelane_b32 v254, s6, 58
	s_mov_b32 s1, s3
	s_mov_b32 s5, s3
	v_writelane_b32 v254, s7, 59
	v_writelane_b32 v254, s0, 6
	s_mov_b32 s20, s51
	s_mov_b32 s21, s51
	v_writelane_b32 v254, s1, 7
	s_mov_b32 s0, s4
	v_writelane_b32 v254, s0, 52
	v_writelane_b32 v255, s51, 0
	s_nop 0
	v_writelane_b32 v254, s1, 53
	s_lshl_b64 s[0:1], s[4:5], 21
	v_writelane_b32 v254, s0, 60
	s_nop 1
	v_writelane_b32 v254, s1, 61
	v_readlane_b32 s0, v253, 43
	v_readlane_b32 s1, v253, 44
	s_nop 0
	v_writelane_b32 v254, s0, 62
	s_nop 1
	v_writelane_b32 v254, s1, 63
	s_branch .LBB0_310
